# P4 scan: streaming (nt) policy on the state stores, full-line writes that the next phase reads from another XCD; less dirty L2 to write back at the barrier
# speedup vs baseline: 1.0190x; 1.0004x over previous
; __device__ __forceinline__ unsigned pk2(float lo, float hi) { return pg8::cvtpk(lo, hi); }
; __device__ __forceinline__ void gla_scan(const Params& P, int G) {
;     ...
;         for (int n = 0; n < 128; ++n) { const size_t unit = (size_t)bh * 128 + n;
;             const u32x2 w = *(const u32x2*)(DS + unit * 32768 + 4 * e4); const f32x4 dd = *(const f32x4*)(decay_g + unit * 128 + d);
;             u32x2 o; o.x = pk2(st[0], st[1]); o.y = pk2(st[2], st[3]); *(u32x2*)(ST + unit * 32768 + 4 * e4) = o;
;             f32x4 in; in[0] = __uint_as_float(w.x << 16); in[1] = __uint_as_float(w.x & 0xffff0000u); in[2] = __uint_as_float(w.y << 16); in[3] = __uint_as_float(w.y & 0xffff0000u);
;             st = dd * st + in; }
.LBB0_485:
	s_add_u32 s26, s58, 0x6800000
	s_addc_u32 s27, s59, 0
	global_load_dwordx2 v[26:27], v2, s[26:27]
	s_add_u32 s26, s58, 0x200000
	s_addc_u32 s27, s59, 0
	global_load_dwordx4 v[58:61], v0, s[26:27]
	s_add_u32 s26, s58, 0x6810000
	s_addc_u32 s27, s59, 0
	global_load_dwordx2 v[28:29], v2, s[26:27]
	s_add_u32 s26, s58, 0x200200
	s_addc_u32 s27, s59, 0
	global_load_dwordx4 v[62:65], v0, s[26:27]
	s_add_u32 s26, s58, 0x6820000
	s_addc_u32 s27, s59, 0
	global_load_dwordx2 v[30:31], v2, s[26:27]
	s_add_u32 s26, s58, 0x200400
	s_addc_u32 s27, s59, 0
	global_load_dwordx4 v[66:69], v0, s[26:27]
	s_add_u32 s26, s58, 0x6830000
	s_addc_u32 s27, s59, 0
	global_load_dwordx2 v[32:33], v2, s[26:27]
	s_add_u32 s26, s58, 0x200600
	s_addc_u32 s27, s59, 0
	global_load_dwordx4 v[70:73], v0, s[26:27]
	s_add_u32 s26, s58, 0x6840000
	s_addc_u32 s27, s59, 0
	global_load_dwordx2 v[34:35], v2, s[26:27]
	s_add_u32 s26, s58, 0x200800
	s_addc_u32 s27, s59, 0
	global_load_dwordx4 v[74:77], v0, s[26:27]
	s_add_u32 s26, s58, 0x6850000
	s_addc_u32 s27, s59, 0
	global_load_dwordx2 v[36:37], v2, s[26:27]
	s_add_u32 s26, s58, 0x200a00
	s_addc_u32 s27, s59, 0
	global_load_dwordx4 v[78:81], v0, s[26:27]
	s_add_u32 s26, s58, 0x6860000
	s_addc_u32 s27, s59, 0
	global_load_dwordx2 v[38:39], v2, s[26:27]
	s_add_u32 s26, s58, 0x200c00
	s_addc_u32 s27, s59, 0
	global_load_dwordx4 v[82:85], v0, s[26:27]
	s_add_u32 s26, s58, 0x6870000
	s_addc_u32 s27, s59, 0
	global_load_dwordx2 v[40:41], v2, s[26:27]
	s_add_u32 s26, s58, 0x200e00
	s_addc_u32 s27, s59, 0
	global_load_dwordx4 v[86:89], v0, s[26:27]
	s_add_u32 s26, s58, 0x6880000
	s_addc_u32 s27, s59, 0
	global_load_dwordx2 v[42:43], v2, s[26:27]
	s_add_u32 s26, s58, 0x201000
	s_addc_u32 s27, s59, 0
	global_load_dwordx4 v[90:93], v0, s[26:27]
	s_add_u32 s26, s58, 0x6890000
	s_addc_u32 s27, s59, 0
	global_load_dwordx2 v[44:45], v2, s[26:27]
	s_add_u32 s26, s58, 0x201200
	s_addc_u32 s27, s59, 0
	global_load_dwordx4 v[94:97], v0, s[26:27]
	s_add_u32 s26, s58, 0x68a0000
	s_addc_u32 s27, s59, 0
	global_load_dwordx2 v[46:47], v2, s[26:27]
	s_add_u32 s26, s58, 0x201400
	s_addc_u32 s27, s59, 0
	global_load_dwordx4 v[98:101], v0, s[26:27]
	s_add_u32 s26, s58, 0x68b0000
	s_addc_u32 s27, s59, 0
	global_load_dwordx2 v[48:49], v2, s[26:27]
	s_add_u32 s26, s58, 0x201600
	s_addc_u32 s27, s59, 0
	global_load_dwordx4 v[102:105], v0, s[26:27]
	s_add_u32 s26, s58, 0x68c0000
	s_addc_u32 s27, s59, 0
	global_load_dwordx2 v[50:51], v2, s[26:27]
	s_add_u32 s26, s58, 0x201800
	s_addc_u32 s27, s59, 0
	global_load_dwordx4 v[106:109], v0, s[26:27]
	s_add_u32 s26, s58, 0x68d0000
	s_addc_u32 s27, s59, 0
	global_load_dwordx2 v[52:53], v2, s[26:27]
	s_add_u32 s26, s58, 0x201a00
	s_addc_u32 s27, s59, 0
	global_load_dwordx4 v[110:113], v0, s[26:27]
	s_add_u32 s26, s58, 0x68e0000
	s_addc_u32 s27, s59, 0
	global_load_dwordx2 v[54:55], v2, s[26:27]
	s_add_u32 s26, s58, 0x201c00
	s_addc_u32 s27, s59, 0
	global_load_dwordx4 v[114:117], v0, s[26:27]
	s_add_u32 s26, s58, 0x68f0000
	s_addc_u32 s27, s59, 0
	global_load_dwordx2 v[56:57], v2, s[26:27]
	s_add_u32 s26, s58, 0x201e00
	s_addc_u32 s27, s59, 0
	global_load_dwordx4 v[118:121], v0, s[26:27]
	v_cvt_pk_bf16_f32 v22, v10, v11
	v_cvt_pk_bf16_f32 v23, v12, v13
	s_add_u32 s26, s58, 0x14800000
	s_addc_u32 s27, s59, 0
	global_store_dwordx2 v2, v[22:23], s[26:27] nt
	s_waitcnt vmcnt(31)
	v_lshlrev_b32_e32 v16, 16, v26
	v_and_b32_e32 v17, 0xffff0000, v26
	v_lshlrev_b32_e32 v18, 16, v27
	v_and_b32_e32 v19, 0xffff0000, v27
	v_pk_fma_f32 v[10:11], v[10:11], v[58:59], v[16:17]
	v_pk_fma_f32 v[12:13], v[12:13], v[60:61], v[18:19]
	v_cvt_pk_bf16_f32 v22, v10, v11
	v_cvt_pk_bf16_f32 v23, v12, v13
	s_add_u32 s26, s58, 0x14810000
	s_addc_u32 s27, s59, 0
	global_store_dwordx2 v2, v[22:23], s[26:27] nt
	s_waitcnt vmcnt(30)
	v_lshlrev_b32_e32 v16, 16, v28
	v_and_b32_e32 v17, 0xffff0000, v28
	v_lshlrev_b32_e32 v18, 16, v29
	v_and_b32_e32 v19, 0xffff0000, v29
	v_pk_fma_f32 v[10:11], v[10:11], v[62:63], v[16:17]
	v_pk_fma_f32 v[12:13], v[12:13], v[64:65], v[18:19]
	v_cvt_pk_bf16_f32 v22, v10, v11
	v_cvt_pk_bf16_f32 v23, v12, v13
	s_add_u32 s26, s58, 0x14820000
	s_addc_u32 s27, s59, 0
	global_store_dwordx2 v2, v[22:23], s[26:27] nt
	s_waitcnt vmcnt(29)
	v_lshlrev_b32_e32 v16, 16, v30
	v_and_b32_e32 v17, 0xffff0000, v30
	v_lshlrev_b32_e32 v18, 16, v31
	v_and_b32_e32 v19, 0xffff0000, v31
	v_pk_fma_f32 v[10:11], v[10:11], v[66:67], v[16:17]
	v_pk_fma_f32 v[12:13], v[12:13], v[68:69], v[18:19]
	v_cvt_pk_bf16_f32 v22, v10, v11
	v_cvt_pk_bf16_f32 v23, v12, v13
	s_add_u32 s26, s58, 0x14830000
	s_addc_u32 s27, s59, 0
	global_store_dwordx2 v2, v[22:23], s[26:27] nt
	s_waitcnt vmcnt(28)
	v_lshlrev_b32_e32 v16, 16, v32
	v_and_b32_e32 v17, 0xffff0000, v32
	v_lshlrev_b32_e32 v18, 16, v33
	v_and_b32_e32 v19, 0xffff0000, v33
	v_pk_fma_f32 v[10:11], v[10:11], v[70:71], v[16:17]
	v_pk_fma_f32 v[12:13], v[12:13], v[72:73], v[18:19]
	v_cvt_pk_bf16_f32 v22, v10, v11
	v_cvt_pk_bf16_f32 v23, v12, v13
	s_add_u32 s26, s58, 0x14840000
	s_addc_u32 s27, s59, 0
	global_store_dwordx2 v2, v[22:23], s[26:27] nt
	s_waitcnt vmcnt(27)
; __device__ __forceinline__ unsigned pk2(float lo, float hi) { return pg8::cvtpk(lo, hi); }
; __device__ __forceinline__ void gla_scan(const Params& P, int G) {
;     ...
;     if (threadIdx.x < 256) for (int gid = blockIdx.x * 256 + threadIdx.x; gid < 8 * 8192; gid += G * 256) {
;         const int bh = gid >> 13, e4 = gid & 8191, d = (4 * e4) & 127;
;         f32x4 st = {0.f, 0.f, 0.f, 0.f};
; #pragma unroll 16
;         for (int n = 0; n < 128; ++n) { const size_t unit = (size_t)bh * 128 + n;
;             const u32x2 w = *(const u32x2*)(DS + unit * 32768 + 4 * e4); const f32x4 dd = *(const f32x4*)(decay_g + unit * 128 + d);
;             u32x2 o; o.x = pk2(st[0], st[1]); o.y = pk2(st[2], st[3]); *(u32x2*)(ST + unit * 32768 + 4 * e4) = o;
;             f32x4 in; in[0] = __uint_as_float(w.x << 16); in[1] = __uint_as_float(w.x & 0xffff0000u); in[2] = __uint_as_float(w.y << 16); in[3] = __uint_as_float(w.y & 0xffff0000u);
;             st = dd * st + in; }
	v_lshlrev_b32_e32 v16, 16, v34
	v_and_b32_e32 v17, 0xffff0000, v34
	v_lshlrev_b32_e32 v18, 16, v35
	v_and_b32_e32 v19, 0xffff0000, v35
	v_pk_fma_f32 v[10:11], v[10:11], v[74:75], v[16:17]
	v_pk_fma_f32 v[12:13], v[12:13], v[76:77], v[18:19]
	v_cvt_pk_bf16_f32 v22, v10, v11
	v_cvt_pk_bf16_f32 v23, v12, v13
	s_add_u32 s26, s58, 0x14850000
	s_addc_u32 s27, s59, 0
	global_store_dwordx2 v2, v[22:23], s[26:27] nt
	s_waitcnt vmcnt(26)
	v_lshlrev_b32_e32 v16, 16, v36
	v_and_b32_e32 v17, 0xffff0000, v36
	v_lshlrev_b32_e32 v18, 16, v37
	v_and_b32_e32 v19, 0xffff0000, v37
	v_pk_fma_f32 v[10:11], v[10:11], v[78:79], v[16:17]
	v_pk_fma_f32 v[12:13], v[12:13], v[80:81], v[18:19]
	v_cvt_pk_bf16_f32 v22, v10, v11
	v_cvt_pk_bf16_f32 v23, v12, v13
	s_add_u32 s26, s58, 0x14860000
	s_addc_u32 s27, s59, 0
	global_store_dwordx2 v2, v[22:23], s[26:27] nt
	s_waitcnt vmcnt(25)
	v_lshlrev_b32_e32 v16, 16, v38
	v_and_b32_e32 v17, 0xffff0000, v38
	v_lshlrev_b32_e32 v18, 16, v39
	v_and_b32_e32 v19, 0xffff0000, v39
	v_pk_fma_f32 v[10:11], v[10:11], v[82:83], v[16:17]
	v_pk_fma_f32 v[12:13], v[12:13], v[84:85], v[18:19]
	v_cvt_pk_bf16_f32 v22, v10, v11
	v_cvt_pk_bf16_f32 v23, v12, v13
	s_add_u32 s26, s58, 0x14870000
	s_addc_u32 s27, s59, 0
	global_store_dwordx2 v2, v[22:23], s[26:27] nt
	s_waitcnt vmcnt(24)
	v_lshlrev_b32_e32 v16, 16, v40
	v_and_b32_e32 v17, 0xffff0000, v40
	v_lshlrev_b32_e32 v18, 16, v41
	v_and_b32_e32 v19, 0xffff0000, v41
	v_pk_fma_f32 v[10:11], v[10:11], v[86:87], v[16:17]
	v_pk_fma_f32 v[12:13], v[12:13], v[88:89], v[18:19]
	v_cvt_pk_bf16_f32 v22, v10, v11
	v_cvt_pk_bf16_f32 v23, v12, v13
	s_add_u32 s26, s58, 0x14880000
	s_addc_u32 s27, s59, 0
	global_store_dwordx2 v2, v[22:23], s[26:27] nt
	s_waitcnt vmcnt(23)
	v_lshlrev_b32_e32 v16, 16, v42
	v_and_b32_e32 v17, 0xffff0000, v42
	v_lshlrev_b32_e32 v18, 16, v43
	v_and_b32_e32 v19, 0xffff0000, v43
	v_pk_fma_f32 v[10:11], v[10:11], v[90:91], v[16:17]
	v_pk_fma_f32 v[12:13], v[12:13], v[92:93], v[18:19]
	v_cvt_pk_bf16_f32 v22, v10, v11
	v_cvt_pk_bf16_f32 v23, v12, v13
	s_add_u32 s26, s58, 0x14890000
	s_addc_u32 s27, s59, 0
	global_store_dwordx2 v2, v[22:23], s[26:27] nt
	s_waitcnt vmcnt(22)
	v_lshlrev_b32_e32 v16, 16, v44
	v_and_b32_e32 v17, 0xffff0000, v44
	v_lshlrev_b32_e32 v18, 16, v45
	v_and_b32_e32 v19, 0xffff0000, v45
	v_pk_fma_f32 v[10:11], v[10:11], v[94:95], v[16:17]
	v_pk_fma_f32 v[12:13], v[12:13], v[96:97], v[18:19]
	v_cvt_pk_bf16_f32 v22, v10, v11
	v_cvt_pk_bf16_f32 v23, v12, v13
	s_add_u32 s26, s58, 0x148a0000
	s_addc_u32 s27, s59, 0
	global_store_dwordx2 v2, v[22:23], s[26:27] nt
	s_waitcnt vmcnt(21)
	v_lshlrev_b32_e32 v16, 16, v46
	v_and_b32_e32 v17, 0xffff0000, v46
	v_lshlrev_b32_e32 v18, 16, v47
	v_and_b32_e32 v19, 0xffff0000, v47
	v_pk_fma_f32 v[10:11], v[10:11], v[98:99], v[16:17]
	v_pk_fma_f32 v[12:13], v[12:13], v[100:101], v[18:19]
	v_cvt_pk_bf16_f32 v22, v10, v11
	v_cvt_pk_bf16_f32 v23, v12, v13
	s_add_u32 s26, s58, 0x148b0000
	s_addc_u32 s27, s59, 0
	global_store_dwordx2 v2, v[22:23], s[26:27] nt
	s_waitcnt vmcnt(20)
	v_lshlrev_b32_e32 v16, 16, v48
	v_and_b32_e32 v17, 0xffff0000, v48
	v_lshlrev_b32_e32 v18, 16, v49
	v_and_b32_e32 v19, 0xffff0000, v49
	v_pk_fma_f32 v[10:11], v[10:11], v[102:103], v[16:17]
	v_pk_fma_f32 v[12:13], v[12:13], v[104:105], v[18:19]
	v_cvt_pk_bf16_f32 v22, v10, v11
	v_cvt_pk_bf16_f32 v23, v12, v13
	s_add_u32 s26, s58, 0x148c0000
	s_addc_u32 s27, s59, 0
	global_store_dwordx2 v2, v[22:23], s[26:27] nt
	s_waitcnt vmcnt(19)
	v_lshlrev_b32_e32 v16, 16, v50
	v_and_b32_e32 v17, 0xffff0000, v50
	v_lshlrev_b32_e32 v18, 16, v51
	v_and_b32_e32 v19, 0xffff0000, v51
	v_pk_fma_f32 v[10:11], v[10:11], v[106:107], v[16:17]
	v_pk_fma_f32 v[12:13], v[12:13], v[108:109], v[18:19]
	v_cvt_pk_bf16_f32 v22, v10, v11
	v_cvt_pk_bf16_f32 v23, v12, v13
	s_add_u32 s26, s58, 0x148d0000
	s_addc_u32 s27, s59, 0
	global_store_dwordx2 v2, v[22:23], s[26:27] nt
	s_waitcnt vmcnt(18)
	v_lshlrev_b32_e32 v16, 16, v52
	v_and_b32_e32 v17, 0xffff0000, v52
	v_lshlrev_b32_e32 v18, 16, v53
	v_and_b32_e32 v19, 0xffff0000, v53
	v_pk_fma_f32 v[10:11], v[10:11], v[110:111], v[16:17]
	v_pk_fma_f32 v[12:13], v[12:13], v[112:113], v[18:19]
	v_cvt_pk_bf16_f32 v22, v10, v11
	v_cvt_pk_bf16_f32 v23, v12, v13
	s_add_u32 s26, s58, 0x148e0000
	s_addc_u32 s27, s59, 0
	global_store_dwordx2 v2, v[22:23], s[26:27] nt
	s_waitcnt vmcnt(17)
	v_lshlrev_b32_e32 v16, 16, v54
	v_and_b32_e32 v17, 0xffff0000, v54
	v_lshlrev_b32_e32 v18, 16, v55
	v_and_b32_e32 v19, 0xffff0000, v55
	v_pk_fma_f32 v[10:11], v[10:11], v[114:115], v[16:17]
	v_pk_fma_f32 v[12:13], v[12:13], v[116:117], v[18:19]
	v_cvt_pk_bf16_f32 v22, v10, v11
	v_cvt_pk_bf16_f32 v23, v12, v13
	s_add_u32 s26, s58, 0x148f0000
	s_addc_u32 s27, s59, 0
	global_store_dwordx2 v2, v[22:23], s[26:27] nt
	s_waitcnt vmcnt(16)
	v_lshlrev_b32_e32 v16, 16, v56
	v_and_b32_e32 v17, 0xffff0000, v56
	v_lshlrev_b32_e32 v18, 16, v57
	v_and_b32_e32 v19, 0xffff0000, v57
	v_pk_fma_f32 v[10:11], v[10:11], v[118:119], v[16:17]
	v_pk_fma_f32 v[12:13], v[12:13], v[120:121], v[18:19]
	s_mov_b64 s[26:27], 0x2000
	v_lshl_add_u64 v[0:1], v[0:1], 0, s[26:27]
	s_mov_b64 s[26:27], 0x100000
	v_lshl_add_u64 v[2:3], v[2:3], 0, s[26:27]
	s_add_i32 s23, s23, -16
	s_cmp_eq_u32 s23, 0
	s_cbranch_scc0 .LBB0_485
	v_add_u32_e32 v14, s3, v14
	s_mov_b32 s23, 0xffff
	v_cmp_lt_i32_e32 vcc, s23, v14
	s_or_b64 s[36:37], vcc, s[36:37]
	v_add_u32_e32 v15, s22, v15
	s_andn2_b64 exec, exec, s[36:37]
	s_cbranch_execnz .LBB0_484
